# SGU: ks>=1 MFMA groups issue their 8 LDS fragment reads together (counted lgkmcnt); x to bf16 conversion loop unrolled x4 with counted waits
# speedup vs baseline: 1.0463x; 1.0024x over previous
; __device__ __forceinline__ void phase_p0(KP p, LAS unsigned char* lds) {
;     ...
;     const float* x = p->in[0]; bf16_t* xb = (bf16_t*)(p->ws + WS_XB);
;     const size_t n8 = (size_t)SEQ * DM / 8;
;     for (size_t i = (size_t)blockIdx.x * 512 + tid; i < n8; i += (size_t)gridDim.x * 512) {
;         const f32x4 a = *(const f32x4*)(x + i * 8), b = *(const f32x4*)(x + i * 8 + 4);
;         u32x4 w; w.x = pk2(a[0], a[1]); w.y = pk2(a[2], a[3]); w.z = pk2(b[0], b[1]); w.w = pk2(b[2], b[3]);
;         *(u32x4*)(xb + i * 8) = w;
;     }
.LBB0_146:
	s_or_b64 exec, exec, s[16:17]
	v_readlane_b32 s6, v241, 0
	v_readlane_b32 s7, v241, 1
	s_mov_b32 s7, 0
	v_writelane_b32 v241, s6, 0
	v_ashrrev_i32_e32 v1, 31, v0
	s_nop 0
	v_writelane_b32 v241, s7, 1
	s_lshl_b64 s[6:7], s[6:7], 9
	v_lshl_add_u64 v[2:3], s[6:7], 0, v[0:1]
	s_mov_b64 s[6:7], 0x400000
	v_cmp_gt_u64_e32 vcc, s[6:7], v[2:3]
	s_and_saveexec_b64 s[6:7], vcc
	s_cbranch_execz .LBB0_149
	s_load_dwordx2 s[16:17], s[14:15], 0x0
	s_load_dwordx2 s[10:11], s[14:15], 0x98
	v_readlane_b32 s20, v241, 0
	v_readlane_b32 s21, v241, 1
	s_mov_b32 s14, s72
	s_mov_b32 s15, s21
	s_lshl_b64 s[8:9], s[14:15], 9
	s_lshl_b64 s[18:19], s[20:21], 13
	s_waitcnt lgkmcnt(0)
	s_add_u32 s10, s10, s18
	s_addc_u32 s11, s11, s19
	v_lshl_add_u64 v[4:5], v[0:1], 4, s[10:11]
	s_mov_b64 s[10:11], 0xc300000
	v_lshl_add_u64 v[4:5], v[4:5], 0, s[10:11]
	s_lshl_b64 s[10:11], s[14:15], 13
	s_lshl_b64 s[18:19], s[20:21], 14
	s_add_u32 s16, s16, s18
	v_lshlrev_b64 v[0:1], 5, v[0:1]
	s_addc_u32 s17, s17, s19
	v_lshl_add_u64 v[0:1], s[16:17], 0, v[0:1]
	v_lshl_add_u64 v[0:1], v[0:1], 0, 16
	s_lshl_b64 s[14:15], s[14:15], 14
	s_mov_b64 s[16:17], 0
	s_mov_b64 s[18:19], 0x3fffff
	s_lshl_b64 s[20:21], s[8:9], 1
	s_add_u32 s20, s20, s8
	s_addc_u32 s21, s21, s9
	s_lshl_b64 s[22:23], s[8:9], 2
	s_lshl_b64 s[24:25], s[14:15], 2
	s_lshl_b64 s[26:27], s[10:11], 2
	s_mov_b64 s[28:29], exec
	v_lshl_add_u64 v[14:15], v[2:3], 0, s[20:21]
	v_cmp_ge_u64_e32 vcc, s[18:19], v[14:15]
	s_and_b64 exec, exec, vcc
	s_cbranch_execz .Lx4_done
.Lx4_loop:
	v_lshl_add_u64 v[14:15], v[0:1], 0, s[14:15]
	v_lshl_add_u64 v[16:17], v[14:15], 0, s[14:15]
	v_lshl_add_u64 v[18:19], v[16:17], 0, s[14:15]
	global_load_dwordx4 v[20:23], v[0:1], off offset:-16
	global_load_dwordx4 v[24:27], v[0:1], off
	global_load_dwordx4 v[28:31], v[14:15], off offset:-16
	global_load_dwordx4 v[32:35], v[14:15], off
	global_load_dwordx4 v[36:39], v[16:17], off offset:-16
	global_load_dwordx4 v[40:43], v[16:17], off
	global_load_dwordx4 v[44:47], v[18:19], off offset:-16
	global_load_dwordx4 v[48:51], v[18:19], off
	v_lshl_add_u64 v[0:1], v[0:1], 0, s[24:25]
	v_lshl_add_u64 v[2:3], v[2:3], 0, s[22:23]
	v_lshl_add_u64 v[14:15], v[4:5], 0, s[10:11]
	v_lshl_add_u64 v[16:17], v[14:15], 0, s[10:11]
	v_lshl_add_u64 v[18:19], v[16:17], 0, s[10:11]
	s_waitcnt vmcnt(6)
	v_cvt_pk_bf16_f32 v20, v20, v21
	v_cvt_pk_bf16_f32 v21, v22, v23
	v_cvt_pk_bf16_f32 v22, v24, v25
	v_cvt_pk_bf16_f32 v23, v26, v27
	global_store_dwordx4 v[4:5], v[20:23], off
	s_waitcnt vmcnt(5)
	v_cvt_pk_bf16_f32 v28, v28, v29
	v_cvt_pk_bf16_f32 v29, v30, v31
	v_cvt_pk_bf16_f32 v30, v32, v33
	v_cvt_pk_bf16_f32 v31, v34, v35
	global_store_dwordx4 v[14:15], v[28:31], off
	s_waitcnt vmcnt(4)
	v_cvt_pk_bf16_f32 v36, v36, v37
	v_cvt_pk_bf16_f32 v37, v38, v39
	v_cvt_pk_bf16_f32 v38, v40, v41
	v_cvt_pk_bf16_f32 v39, v42, v43
	global_store_dwordx4 v[16:17], v[36:39], off
	s_waitcnt vmcnt(3)
	v_cvt_pk_bf16_f32 v44, v44, v45
	v_cvt_pk_bf16_f32 v45, v46, v47
	v_cvt_pk_bf16_f32 v46, v48, v49
	v_cvt_pk_bf16_f32 v47, v50, v51
	global_store_dwordx4 v[18:19], v[44:47], off
	v_lshl_add_u64 v[4:5], v[4:5], 0, s[26:27]
	v_lshl_add_u64 v[14:15], v[2:3], 0, s[20:21]
	v_cmp_ge_u64_e32 vcc, s[18:19], v[14:15]
	s_and_b64 exec, exec, vcc
	s_cbranch_execnz .Lx4_loop
.Lx4_done:
	s_mov_b64 exec, s[28:29]
	v_cmp_ge_u64_e32 vcc, s[18:19], v[2:3]
	s_and_b64 exec, exec, vcc
	s_cbranch_execz .LBB0_149

; #define LAS __attribute__((address_space(3)))
; __device__ __forceinline__ f32x4 mfma16(bf16x8 a, bf16x8 b, f32x4 c) { return __builtin_amdgcn_mfma_f32_16x16x32_bf16(a, b, c, 0, 0, 0); }
; __device__ __forceinline__ void sgu_item(KP p, LAS unsigned char* lds, int l, int n) {
;     ...
;             for (int ks = 0; ks < 4; ++ks) if (ks < nks) { const int s0 = ks * 32 + fq * 8;
;                 u32x4 bw;
;                 bw.x = pk2(s0 + 0 <= t ? w0[ks][0] : 0.f, s0 + 1 <= t ? w0[ks][1] : 0.f); bw.y = pk2(s0 + 2 <= t ? w0[ks][2] : 0.f, s0 + 3 <= t ? w0[ks][3] : 0.f);
;                 bw.z = pk2(s0 + 4 <= t ? w1[ks][0] : 0.f, s0 + 5 <= t ? w1[ks][1] : 0.f); bw.w = pk2(s0 + 6 <= t ? w1[ks][2] : 0.f, s0 + 7 <= t ? w1[ks][3] : 0.f);
;                 const bf16x8 bf = __builtin_bit_cast(bf16x8, bw);
; #pragma unroll
;                 for (int dt = 0; dt < 8; ++dt) { const bf16x8 af = *(const LAS bf16x8*)(vnT + (hl * 128 + dt * 16 + fr) * 136 + s0);
;                     acc[dt] = mfma16(af, bf, acc[dt]); } }
.LBB0_537:
	v_cvt_pk_bf16_f32 v86, v86, s0
	v_cmp_le_u32_e32 vcc, v139, v180
	v_cvt_pk_bf16_f32 v87, v87, s0
	v_cvt_pk_bf16_f32 v82, v82, s0
	v_cndmask_b32_e32 v86, 0, v86, vcc
	v_cmp_lt_u32_e32 vcc, v139, v180
	v_cvt_pk_bf16_f32 v83, v83, s0
	s_nop 0
	v_cndmask_b32_e32 v87, 0, v87, vcc
	v_perm_b32 v86, v87, v86, s60
	v_cvt_pk_bf16_f32 v87, v88, s0
	v_cmp_le_u32_e32 vcc, v148, v180
	v_cvt_pk_bf16_f32 v88, v89, s0
	s_nop 0
	v_cndmask_b32_e32 v87, 0, v87, vcc
	v_cmp_le_u32_e32 vcc, v149, v180
	s_nop 1
	v_cndmask_b32_e32 v88, 0, v88, vcc
	v_cmp_le_u32_e32 vcc, v150, v180
	v_perm_b32 v87, v88, v87, s60
	s_nop 0
	v_cndmask_b32_e32 v82, 0, v82, vcc
	v_cmp_le_u32_e32 vcc, v151, v180
	s_nop 1
	v_cndmask_b32_e32 v83, 0, v83, vcc
	v_perm_b32 v88, v83, v82, s60
	v_cvt_pk_bf16_f32 v82, v84, s0
	v_cmp_le_u32_e32 vcc, v152, v180
	v_cvt_pk_bf16_f32 v83, v85, s0
	s_nop 0
	v_cndmask_b32_e32 v82, 0, v82, vcc
	v_cmp_le_u32_e32 vcc, v153, v180
	s_nop 1
	v_cndmask_b32_e32 v83, 0, v83, vcc
	v_perm_b32 v89, v83, v82, s60
	ds_read_b128 v[186:189], v179 offset:64
	ds_read_b128 v[190:193], v179 offset:4416
	ds_read_b128 v[194:197], v179 offset:8768
	ds_read_b128 v[198:201], v179 offset:13120
	ds_read_b128 v[202:205], v179 offset:17472
	ds_read_b128 v[206:209], v179 offset:21824
	ds_read_b128 v[210:213], v179 offset:26176
	ds_read_b128 v[214:217], v179 offset:30528
	s_waitcnt lgkmcnt(7)
	v_mfma_f32_16x16x32_bf16 v[62:65], v[186:189], v[86:89], v[62:65]
	s_waitcnt lgkmcnt(6)
	v_mfma_f32_16x16x32_bf16 v[58:61], v[190:193], v[86:89], v[58:61]
	s_waitcnt lgkmcnt(5)
	v_mfma_f32_16x16x32_bf16 v[54:57], v[194:197], v[86:89], v[54:57]
	s_waitcnt lgkmcnt(4)
	v_mfma_f32_16x16x32_bf16 v[50:53], v[198:201], v[86:89], v[50:53]
	s_waitcnt lgkmcnt(3)
	v_mfma_f32_16x16x32_bf16 v[46:49], v[202:205], v[86:89], v[46:49]
	s_waitcnt lgkmcnt(2)
	v_mfma_f32_16x16x32_bf16 v[42:45], v[206:209], v[86:89], v[42:45]
	s_waitcnt lgkmcnt(1)
	v_mfma_f32_16x16x32_bf16 v[38:41], v[210:213], v[86:89], v[38:41]
	s_waitcnt lgkmcnt(0)
	v_mfma_f32_16x16x32_bf16 v[34:37], v[214:217], v[86:89], v[34:37]
	s_andn2_b64 vcc, exec, s[88:89]
	s_cbranch_vccnz .LBB0_536
.LBB0_538:
	v_cvt_pk_bf16_f32 v74, v74, s0
	v_cmp_le_u32_e32 vcc, v154, v180
	v_cvt_pk_bf16_f32 v75, v75, s0
	s_nop 0
	v_cndmask_b32_e32 v74, 0, v74, vcc
	v_cmp_lt_u32_e32 vcc, v154, v180
	s_nop 1
	v_cndmask_b32_e32 v75, 0, v75, vcc
	v_perm_b32 v74, v75, v74, s60
	v_cvt_pk_bf16_f32 v75, v76, s0
	v_cmp_le_u32_e32 vcc, v155, v180
	v_cvt_pk_bf16_f32 v76, v77, s0
	v_cvt_pk_bf16_f32 v77, v79, s0
	v_cndmask_b32_e32 v75, 0, v75, vcc
	v_cmp_le_u32_e32 vcc, v156, v180
	s_nop 1
	v_cndmask_b32_e32 v76, 0, v76, vcc
	v_perm_b32 v75, v76, v75, s60
	v_cvt_pk_bf16_f32 v76, v78, s0
	v_cmp_le_u32_e32 vcc, v157, v180
	v_cvt_pk_bf16_f32 v78, v81, s0
	s_nop 0
	v_cndmask_b32_e32 v76, 0, v76, vcc
	v_cmp_le_u32_e32 vcc, v158, v180
	s_nop 1
	v_cndmask_b32_e32 v77, 0, v77, vcc
	v_perm_b32 v76, v77, v76, s60
	v_cvt_pk_bf16_f32 v77, v80, s0
	v_cmp_le_u32_e32 vcc, v159, v180
	s_nop 1
	v_cndmask_b32_e32 v77, 0, v77, vcc
	v_cmp_le_u32_e32 vcc, v160, v180
	s_nop 1
	v_cndmask_b32_e32 v78, 0, v78, vcc
	v_perm_b32 v77, v78, v77, s60
	ds_read_b128 v[186:189], v179 offset:128
	ds_read_b128 v[190:193], v179 offset:4480
	ds_read_b128 v[194:197], v179 offset:8832
	ds_read_b128 v[198:201], v179 offset:13184
	ds_read_b128 v[202:205], v179 offset:17536
	ds_read_b128 v[206:209], v179 offset:21888
	ds_read_b128 v[210:213], v179 offset:26240
	ds_read_b128 v[214:217], v179 offset:30592
	s_waitcnt lgkmcnt(7)
	v_mfma_f32_16x16x32_bf16 v[62:65], v[186:189], v[74:77], v[62:65]
	s_waitcnt lgkmcnt(6)
	v_mfma_f32_16x16x32_bf16 v[58:61], v[190:193], v[74:77], v[58:61]
	s_waitcnt lgkmcnt(5)
	v_mfma_f32_16x16x32_bf16 v[54:57], v[194:197], v[74:77], v[54:57]
	s_waitcnt lgkmcnt(4)
	v_mfma_f32_16x16x32_bf16 v[50:53], v[198:201], v[74:77], v[50:53]
	s_waitcnt lgkmcnt(3)
	v_mfma_f32_16x16x32_bf16 v[46:49], v[202:205], v[74:77], v[46:49]
	s_waitcnt lgkmcnt(2)
	v_mfma_f32_16x16x32_bf16 v[42:45], v[206:209], v[74:77], v[42:45]
	s_waitcnt lgkmcnt(1)
	v_mfma_f32_16x16x32_bf16 v[38:41], v[210:213], v[74:77], v[38:41]
	s_waitcnt lgkmcnt(0)
	v_mfma_f32_16x16x32_bf16 v[34:37], v[214:217], v[74:77], v[34:37]
	s_andn2_b64 vcc, exec, s[46:47]
	s_cbranch_vccnz .LBB0_527
.LBB0_539:
	v_cvt_pk_bf16_f32 v70, v70, s0
	v_cmp_le_u32_e32 vcc, v161, v180
	v_cvt_pk_bf16_f32 v71, v71, s0
	v_cvt_pk_bf16_f32 v66, v66, s0
	v_cndmask_b32_e32 v70, 0, v70, vcc
	v_cmp_lt_u32_e32 vcc, v161, v180
	v_cvt_pk_bf16_f32 v67, v67, s0
	s_nop 0
	v_cndmask_b32_e32 v71, 0, v71, vcc
	v_perm_b32 v70, v71, v70, s60
	v_cvt_pk_bf16_f32 v71, v72, s0
	v_cmp_le_u32_e32 vcc, v162, v180
	v_cvt_pk_bf16_f32 v72, v73, s0
	s_nop 0
	v_cndmask_b32_e32 v71, 0, v71, vcc
	v_cmp_le_u32_e32 vcc, v163, v180
	s_nop 1
	v_cndmask_b32_e32 v72, 0, v72, vcc
	v_cmp_le_u32_e32 vcc, v164, v180
	v_perm_b32 v71, v72, v71, s60
	s_nop 0
	v_cndmask_b32_e32 v66, 0, v66, vcc
	v_cmp_le_u32_e32 vcc, v165, v180
	s_nop 1
	v_cndmask_b32_e32 v67, 0, v67, vcc
	v_perm_b32 v72, v67, v66, s60
	v_cvt_pk_bf16_f32 v66, v68, s0
	v_cmp_le_u32_e32 vcc, v174, v180
	v_cvt_pk_bf16_f32 v67, v69, s0
	s_nop 0
	v_cndmask_b32_e32 v66, 0, v66, vcc
	v_cmp_le_u32_e32 vcc, v175, v180
	s_nop 1
	v_cndmask_b32_e32 v67, 0, v67, vcc
	v_perm_b32 v73, v67, v66, s60
	ds_read_b128 v[186:189], v179 offset:192
	ds_read_b128 v[190:193], v179 offset:4544
	ds_read_b128 v[194:197], v179 offset:8896
	ds_read_b128 v[198:201], v179 offset:13248
	ds_read_b128 v[202:205], v179 offset:17600
	ds_read_b128 v[206:209], v179 offset:21952
	ds_read_b128 v[210:213], v179 offset:26304
	ds_read_b128 v[214:217], v179 offset:30656
	s_waitcnt lgkmcnt(7)
	v_mfma_f32_16x16x32_bf16 v[62:65], v[186:189], v[70:73], v[62:65]
	s_waitcnt lgkmcnt(6)
	v_mfma_f32_16x16x32_bf16 v[58:61], v[190:193], v[70:73], v[58:61]
	s_waitcnt lgkmcnt(5)
	v_mfma_f32_16x16x32_bf16 v[54:57], v[194:197], v[70:73], v[54:57]
	s_waitcnt lgkmcnt(4)
	v_mfma_f32_16x16x32_bf16 v[50:53], v[198:201], v[70:73], v[50:53]
	s_waitcnt lgkmcnt(3)
	v_mfma_f32_16x16x32_bf16 v[46:49], v[202:205], v[70:73], v[46:49]
	s_waitcnt lgkmcnt(2)
	v_mfma_f32_16x16x32_bf16 v[42:45], v[206:209], v[70:73], v[42:45]
	s_waitcnt lgkmcnt(1)
	v_mfma_f32_16x16x32_bf16 v[38:41], v[210:213], v[70:73], v[38:41]
	s_waitcnt lgkmcnt(0)
	v_mfma_f32_16x16x32_bf16 v[34:37], v[214:217], v[70:73], v[34:37]
	s_branch .LBB0_527
